# v12wgstag
# baseline (speedup 1.0000x reference)
; __device__ __forceinline__ int obid() { int t = blockIdx.x; asm volatile("" : "+s"(t)); return t; }
; __device__ __forceinline__ int ogdim() { int t = gridDim.x; asm volatile("" : "+s"(t)); return t; }
; #define LOAD_PARAMS(q_) const __attribute__((address_space(4))) Params* kq_##q_ = (const __attribute__((address_space(4))) Params*)__builtin_amdgcn_kernarg_segment_ptr(); asm volatile("" : "+s"(kq_##q_)); \
;     const Params q_ = *kq_##q_
; __global__ void __launch_bounds__(NTHREADS, 2) mega_fwd(Params p_unused) {
;     ...
;     for (int step = 0; step < NBATCH * DEPTH * 7; ++step) {
;         int st = step; asm volatile("" : "+s"(st));
;         LOAD_PARAMS(p); unsigned char* ws = p.ws; asm volatile("" : "+s"(ws));
;         const int G = ogdim(), bx = obid();
;         const int bl = st / 7, ph = st - bl * 7, b = bl >> 1, l = bl & 1;
;         bf16_t* xb = (bf16_t*)(ws + O_XB); bf16_t* proj = (bf16_t*)(ws + O_PROJ);
;         const float* xin = p.x + (size_t)b * TB * DM; float* hout = p.out + (size_t)b * TB * DM; const float* hin = l == 0 ? xin : hout;
;         if (ph == 0) {
;     ...
;         } else if (ph == 5) {
;     ...
;             { pg8::Gemm g{(const bf16_t*)(ws + O_YA8), (const bf16_t*)(ws + O_WA8 + (size_t)l * 2048 * 1024), TB, DM, 512, 512, 0}; pg8::StaticOrder S; S.init(TB, DM, G, bx);
;               pg8::EpiBranch E{(const unsigned char*)(proj + GATE0), xb, 1, 1.f / 1024.f}; pg8::gemm_phase<pg8::EpiBranch, 2>(lds, g, S, E); }
.LBB0_260:
	v_readlane_b32 s16, v253, 11
	s_mov_b32 s34, s64
	v_readlane_b32 s17, v253, 12
	s_load_dwordx4 s[12:15], s[16:17], 0x88
	s_mov_b32 s0, s96
	s_waitcnt lgkmcnt(0)
	s_mov_b64 s[40:41], s[14:15]
	s_nop 0
	v_writelane_b32 v253, s0, 40
	s_nop 0
	v_readlane_b32 s0, v253, 0
	s_nop 1
	v_writelane_b32 v253, s0, 15
	s_load_dwordx2 s[0:1], s[16:17], 0x0
	v_writelane_b32 v254, s16, 44
	s_load_dwordx8 s[84:91], s[16:17], 0x50
	s_nop 0
	v_writelane_b32 v254, s17, 45
	s_mul_hi_i32 s16, s34, 0x92492493
	s_add_i32 s16, s16, s34
	s_waitcnt lgkmcnt(0)
	v_writelane_b32 v254, s84, 46
	s_lshr_b32 s17, s16, 31
	s_ashr_i32 s16, s16, 2
	v_writelane_b32 v254, s85, 47
	v_writelane_b32 v254, s86, 48
	v_writelane_b32 v254, s87, 49
	v_writelane_b32 v254, s88, 50
	v_writelane_b32 v254, s89, 51
	v_writelane_b32 v254, s90, 52
	s_add_i32 s16, s16, s17
	v_writelane_b32 v254, s91, 53
	s_mul_i32 s17, s16, -7
	v_writelane_b32 v254, s34, 54
	s_add_i32 s35, s17, s34
	s_ashr_i32 s42, s16, 1
	s_and_b32 s34, s16, 1
	s_add_u32 s74, s40, 0xa200000
	s_addc_u32 s75, s41, 0
	s_add_u32 s16, s40, 0xe200000
	v_writelane_b32 v254, s40, 55
	s_addc_u32 s17, s41, 0
	v_writelane_b32 v253, s16, 13
	v_writelane_b32 v254, s41, 56
	s_ashr_i32 s43, s42, 31
	v_writelane_b32 v253, s17, 14
	v_writelane_b32 v254, s42, 57
	s_lshl_b64 s[16:17], s[42:43], 27
	s_add_u32 s0, s0, s16
	s_addc_u32 s1, s1, s17
	s_add_u32 s12, s12, s16
	s_addc_u32 s13, s13, s17
	s_cmp_eq_u32 s34, 0
	s_cselect_b32 s1, s1, s13
	v_writelane_b32 v253, s12, 36
	s_cselect_b32 s0, s0, s12
	v_writelane_b32 v254, s43, 58
	v_writelane_b32 v253, s13, 37
	v_writelane_b32 v253, s0, 26
	v_writelane_b32 v254, s34, 59
	s_mov_b64 s[12:13], -1
	v_writelane_b32 v253, s1, 27
	v_writelane_b32 v253, s64, 3
	s_mov_b64 s[0:1], 0
	v_writelane_b32 v253, s74, 24
	v_writelane_b32 v254, s0, 60
	s_cmp_eq_u32 s35, 1
	s_cbranch_scc1 .Lmy_dchk
	s_branch .Lmy_nodelay
.Lmy_dchk:
	v_readlane_b32 s98, v253, 0
	s_nop 3
	s_bitcmp1_b32 s98, 3
	s_cbranch_scc0 .Lmy_nodelay
	s_memrealtime s[98:99]
	s_waitcnt lgkmcnt(0)
	s_add_u32 s101, s98, 800
.Lmy_dl:
	s_memrealtime s[98:99]
	s_waitcnt lgkmcnt(0)
	s_sub_u32 s99, s98, s101
	s_cmp_lt_i32 s99, 0
	s_cbranch_scc1 .Lmy_dl
.Lmy_nodelay:
	s_cmp_lt_i32 s35, 3
	v_writelane_b32 v253, s75, 25
	v_writelane_b32 v254, s1, 61
	v_writelane_b32 v253, s35, 9
	s_cbranch_scc1 .LBB0_479
	v_readlane_b32 s0, v253, 9
	s_cmp_gt_i32 s0, 3
	s_cbranch_scc0 .LBB0_289
	s_cmp_gt_i32 s0, 4
	s_cbranch_scc0 .LBB0_290
	s_cmp_eq_u32 s0, 5
	s_mov_b64 s[0:1], -1
	s_cbranch_scc0 .LBB0_317
	v_readlane_b32 s0, v254, 55
	v_readlane_b32 s1, v254, 56
	s_add_u32 s0, s0, 0xe203a00
	s_addc_u32 s1, s1, 0
	v_writelane_b32 v253, s0, 38
	v_mov_b32_e32 v9, v199
	s_mov_b64 s[40:41], -1
	v_writelane_b32 v253, s1, 39
	v_readfirstlane_b32 s1, v9
	v_readlane_b32 s0, v253, 15
	s_cmpk_lt_i32 s0, 0x200
	s_cselect_b64 s[72:73], -1, 0
	s_and_b64 vcc, exec, s[72:73]
	s_cbranch_vccnz .LBB0_266
	v_readlane_b32 s0, v253, 15
	s_and_b32 s12, s0, 7
	s_lshr_b32 s13, s0, 3
	v_readlane_b32 s0, v253, 40
	s_ashr_i32 s17, s0, 31
	s_mov_b32 s16, s81
	s_mov_b64 s[40:41], 0
